# out-norm gains loaded once per item; first load segment ds_reads hoisted to the unit-loop header
# baseline (speedup 1.0000x reference)
; template <class Epi, class Sched, bool ALIGN_EPI>
; __device__ __forceinline__ void gemm_phase(LAS unsigned char* lds, const Gemm g, const Sched& S, const Epi& E) {
;     ...
;         const bool has_next = S.next(ui + 1, nxt);
;         const char* nA = has_next ? (const char*)g.A + (size_t)nxt.pm * tstepA : cA; const char* nB = has_next ? (const char*)g.Bt + (size_t)nxt.pn * tstepB : cB;
.LBB0_604:
	ds_read_b128 v[154:157], v148
	ds_read_b128 v[158:161], v148 offset:1024
	ds_read_b128 v[162:165], v148 offset:2048
	ds_read_b128 v[166:169], v148 offset:3072
	ds_read_b128 v[170:173], v149
	ds_read_b128 v[174:177], v149 offset:1024
	ds_read_b128 v[178:181], v149 offset:2048
	ds_read_b128 v[182:185], v149 offset:3072
	ds_read_b128 v[186:189], v150
	ds_read_b128 v[190:193], v150 offset:1024
	ds_read_b128 v[194:197], v150 offset:2048
	ds_read_b128 v[198:201], v150 offset:3072
	ds_read_b128 v[202:205], v150 offset:4096
	ds_read_b128 v[206:209], v150 offset:5120
	ds_read_b128 v[210:213], v150 offset:6144
	ds_read_b128 v[214:217], v150 offset:7168
	s_add_i32 s43, s43, 1
	s_mul_i32 s2, s43, s0
	s_mul_hi_u32 s3, s43, s76
	s_add_i32 s3, s3, s2
	s_mul_i32 s2, s43, s76
	s_add_u32 s16, s2, s97
	s_addc_u32 s17, s3, s1
	v_cmp_gt_i64_e32 vcc, s[16:17], v[142:143]
	v_cmp_lt_i64_e64 s[2:3], s[16:17], v[140:141]
	s_cbranch_vccnz .LBB0_606
	s_ashr_i32 s12, s16, 31
	s_lshr_b32 s12, s12, 29
	s_add_i32 s12, s16, s12
	s_ashr_i32 s13, s12, 3
	s_and_b32 s12, s12, -8
	s_sub_i32 s12, s16, s12
	s_cmp_lt_i32 s12, 0
	s_cselect_b32 s14, s34, 0x160
	s_mul_i32 s12, s12, s14
	s_add_i32 s12, s12, s13
	s_mul_hi_i32 s13, s12, 0x2e8ba2e9
	s_lshr_b32 s14, s13, 31
	s_ashr_i32 s13, s13, 4
	s_add_i32 s13, s13, s14
	s_lshl_b32 s14, s13, 2
	s_sub_i32 s15, 0x80, s14
	s_min_i32 s15, s15, 4
	s_abs_i32 s16, s15
	v_cvt_f32_u32_e32 v0, s16
	s_sub_i32 s18, 0, s16
	s_mulk_i32 s13, 0x58
	s_sub_i32 s13, s12, s13
	v_rcp_iflag_f32_e32 v0, v0
	s_abs_i32 s12, s13
	s_xor_b32 s17, s13, s15
	s_ashr_i32 s17, s17, 31
	v_mul_f32_e32 v0, 0x4f7ffffe, v0
	v_cvt_u32_f32_e32 v0, v0
	s_mov_b32 s44, s43
	v_readfirstlane_b32 s19, v0
	s_mul_i32 s18, s18, s19
	s_mul_hi_u32 s18, s19, s18
	s_add_i32 s19, s19, s18
	s_mul_hi_u32 s18, s12, s19
	s_mul_i32 s19, s18, s16
	s_sub_i32 s12, s12, s19
	s_add_i32 s26, s18, 1
	s_sub_i32 s19, s12, s16
	s_cmp_ge_u32 s12, s16
	s_cselect_b32 s18, s26, s18
	s_cselect_b32 s12, s19, s12
	s_add_i32 s19, s18, 1
	s_cmp_ge_u32 s12, s16
	s_cselect_b32 s12, s19, s18
	s_xor_b32 s12, s12, s17
	s_sub_i32 s12, s12, s17
	s_mul_i32 s15, s12, s15
	s_sub_i32 s13, s13, s15
	s_add_i32 s14, s14, s13
.LBB0_606:
	s_ashr_i32 s15, s14, 31
	s_lshl_b64 s[16:17], s[14:15], 19
	s_add_u32 s16, s29, s16
	s_addc_u32 s17, s30, s17
	s_and_b64 s[18:19], s[2:3], exec
	s_cselect_b32 s15, s17, s23
	s_cselect_b32 s48, s16, s22
	s_ashr_i32 s13, s12, 31
	s_lshl_b64 s[18:19], s[12:13], 19
	s_add_u32 s18, s31, s18
	s_addc_u32 s19, s33, s19
	s_and_b64 s[26:27], s[2:3], exec
	s_cselect_b32 s13, s19, s25
	s_cselect_b32 s49, s18, s24
	s_add_u32 s22, s22, 0x40080
	s_addc_u32 s23, s23, 0
	s_add_u32 s50, s24, 0x100
	v_mov_b32_e32 v0, 0
	s_addc_u32 s51, s25, 0
	s_mov_b32 s52, -2
	s_add_u32 s24, s22, 0xfffc0080
	s_addc_u32 s25, s23, -1
	s_cmp_eq_u32 s52, 12
	s_cselect_b32 s27, s15, s25
	s_cselect_b32 s26, s48, s24
	s_cselect_b32 s25, s13, s51
	s_cselect_b32 s24, s49, s50
	v_lshl_add_u64 v[218:219], s[22:23], 0, v[136:137]
	s_add_i32 m0, s21, 0xc000
	s_nop 0
	global_load_lds_dwordx4 v[218:219], off
	v_lshl_add_u64 v[218:219], s[22:23], 0, v[138:139]
	s_add_i32 m0, s21, 0xe000
	s_nop 0
	global_load_lds_dwordx4 v[218:219], off
	s_cmp_eq_u32 s101, 1
	s_cbranch_scc1 .Lpk607_r1
	s_waitcnt vmcnt(8)
	s_branch .Lpk607_j1

;     __host__ __device__ bool next(int i, Unit& u) const {
;         const long L = (long)i * G + c; if (L >= nwg) return false;
;         int wgid = (int)L; { const int q = nwg / NXCD, r = nwg % NXCD, xcd = wgid % NXCD, off = wgid / NXCD; wgid = (xcd < r ? xcd * (q + 1) : r * (q + 1) + (xcd - r) * q) + off; }
;         const int nig = WGM * nN, gid = wgid / nig, fm = gid * WGM, gsz = (nM - fm) < WGM ? (nM - fm) : WGM;
;         u.pm = fm + ((wgid % nig) % gsz); u.pn = (wgid % nig) / gsz; u.idx = i; return true;
; template <class Epi, class Sched, bool ALIGN_EPI>
; __device__ __forceinline__ void gemm_phase(LAS unsigned char* lds, const Gemm g, const Sched& S, const Epi& E) {
;     ...
;         const bool has_next = S.next(ui + 1, nxt);
;         const char* nA = has_next ? (const char*)g.A + (size_t)nxt.pm * tstepA : cA; const char* nB = has_next ? (const char*)g.Bt + (size_t)nxt.pn * tstepB : cB;
.LBB0_705:
	ds_read_b128 v[128:131], v191
	ds_read_b128 v[132:135], v191 offset:1024
	ds_read_b128 v[136:139], v191 offset:2048
	ds_read_b128 v[140:143], v191 offset:3072
	ds_read_b128 v[144:147], v192
	ds_read_b128 v[148:151], v192 offset:1024
	ds_read_b128 v[170:173], v192 offset:2048
	ds_read_b128 v[174:177], v192 offset:3072
	ds_read_b128 v[178:181], v193
	ds_read_b128 v[182:185], v193 offset:1024
	ds_read_b128 v[196:199], v193 offset:2048
	ds_read_b128 v[200:203], v193 offset:3072
	ds_read_b128 v[204:207], v193 offset:4096
	ds_read_b128 v[208:211], v193 offset:5120
	ds_read_b128 v[212:215], v193 offset:6144
	ds_read_b128 v[216:219], v193 offset:7168
	s_add_i32 s31, s31, 1
	s_mul_i32 s4, s31, s35
	s_mul_hi_u32 s5, s31, s36
	s_add_i32 s5, s5, s4
	s_mul_i32 s4, s31, s36
	s_add_u32 s4, s4, s97
	s_addc_u32 s5, s5, s37
	v_cmp_gt_i64_e32 vcc, s[4:5], v[168:169]
	v_cmp_lt_i64_e64 s[6:7], s[4:5], v[166:167]
	s_cbranch_vccnz .LBB0_711
	s_ashr_i32 s5, s4, 31
	s_lshr_b32 s5, s5, 29
	s_add_i32 s18, s4, s5
	s_and_b32 s5, s18, -8
	s_sub_i32 s19, s4, s5
	s_cmp_gt_i32 s19, -1
	s_mov_b64 s[4:5], -1
	s_cbranch_scc0 .LBB0_708
	s_lshl_b32 s24, s19, 6
	s_mov_b64 s[4:5], 0

.LBB0_715:
	s_add_u32 s20, s20, 0xb0080
	s_addc_u32 s21, s21, 0
	s_add_u32 s44, s22, 0x100
	v_mov_b32_e32 v0, 0
	s_addc_u32 s45, s23, 0
	s_mov_b32 s47, -2
	s_waitcnt lgkmcnt(0)
	s_add_u32 s22, s20, 0xfff50080
	s_addc_u32 s23, s21, -1
	s_cmp_eq_u32 s47, 40
	s_cselect_b32 s25, s7, s23
	s_cselect_b32 s24, s6, s22
	s_cselect_b32 s23, s19, s45
	s_cselect_b32 s22, s18, s44
	v_lshl_add_u64 v[186:187], s[20:21], 0, v[162:163]
	s_add_i32 m0, s27, 0xc000
	s_nop 0
	global_load_lds_dwordx4 v[186:187], off
	v_lshl_add_u64 v[186:187], s[20:21], 0, v[164:165]
	s_add_i32 m0, s27, 0xe000
	s_nop 0
	global_load_lds_dwordx4 v[186:187], off
	s_cmp_eq_u32 s101, 1
	s_cbranch_scc1 .Lpk716_r1
	s_waitcnt vmcnt(8)
	s_branch .Lpk716_j1

; template <class Epi, class Sched, bool ALIGN_EPI>
; __device__ __forceinline__ void gemm_phase(LAS unsigned char* lds, const Gemm g, const Sched& S, const Epi& E) {
;     ...
;         const bool has_next = S.next(ui + 1, nxt);
;         const char* nA = has_next ? (const char*)g.A + (size_t)nxt.pm * tstepA : cA; const char* nB = has_next ? (const char*)g.Bt + (size_t)nxt.pn * tstepB : cB;
.LBB0_871:
	ds_read_b128 v[146:149], v158
	ds_read_b128 v[162:165], v158 offset:1024
	ds_read_b128 v[166:169], v158 offset:2048
	ds_read_b128 v[170:173], v158 offset:3072
	ds_read_b128 v[174:177], v159
	ds_read_b128 v[178:181], v159 offset:1024
	ds_read_b128 v[182:185], v159 offset:2048
	ds_read_b128 v[186:189], v159 offset:3072
	ds_read_b128 v[190:193], v160
	ds_read_b128 v[194:197], v160 offset:1024
	ds_read_b128 v[198:201], v160 offset:2048
	ds_read_b128 v[202:205], v160 offset:3072
	ds_read_b128 v[206:209], v160 offset:4096
	ds_read_b128 v[210:213], v160 offset:5120
	ds_read_b128 v[214:217], v160 offset:6144
	ds_read_b128 v[218:221], v160 offset:7168
	s_add_i32 s48, s48, 1
	s_mul_i32 s4, s48, s0
	s_mul_hi_u32 s5, s48, s76
	s_add_i32 s5, s5, s4
	s_mul_i32 s4, s48, s76
	s_add_u32 s22, s4, s97
	s_addc_u32 s23, s5, s1
	v_cmp_gt_i64_e32 vcc, s[22:23], v[144:145]
	v_cmp_lt_i64_e64 s[4:5], s[22:23], v[142:143]
	s_cbranch_vccnz .LBB0_873
	s_ashr_i32 s18, s22, 31
	s_lshr_b32 s18, s18, 29
	s_add_i32 s18, s22, s18
	s_ashr_i32 s19, s18, 3
	s_and_b32 s18, s18, -8
	s_sub_i32 s18, s22, s18
	s_cmp_lt_i32 s18, 0
	s_cselect_b32 s20, s43, 0x120
	s_mul_i32 s18, s18, s20
	s_add_i32 s18, s18, s19
	s_mul_hi_i32 s19, s18, 0x38e38e39
	s_lshr_b32 s20, s19, 31
	s_ashr_i32 s19, s19, 4
	s_add_i32 s19, s19, s20
	s_lshl_b32 s20, s19, 2
	s_sub_i32 s21, 0x80, s20
	s_min_i32 s21, s21, 4
	s_abs_i32 s22, s21
	v_cvt_f32_u32_e32 v0, s22
	s_sub_i32 s24, 0, s22
	s_mulk_i32 s19, 0x48
	s_sub_i32 s19, s18, s19
	v_rcp_iflag_f32_e32 v0, v0
	s_abs_i32 s18, s19
	s_xor_b32 s23, s19, s21
	s_ashr_i32 s23, s23, 31
	v_mul_f32_e32 v0, 0x4f7ffffe, v0
	v_cvt_u32_f32_e32 v0, v0
	s_mov_b32 s49, s48
	v_readfirstlane_b32 s25, v0
	s_mul_i32 s24, s24, s25
	s_mul_hi_u32 s24, s25, s24
	s_add_i32 s25, s25, s24
	s_mul_hi_u32 s24, s18, s25
	s_mul_i32 s25, s24, s22
	s_sub_i32 s18, s18, s25
	s_add_i32 s30, s24, 1
	s_sub_i32 s25, s18, s22
	s_cmp_ge_u32 s18, s22
	s_cselect_b32 s24, s30, s24
	s_cselect_b32 s18, s25, s18
	s_add_i32 s25, s24, 1
	s_cmp_ge_u32 s18, s22
	s_cselect_b32 s18, s25, s24
	s_xor_b32 s18, s18, s23
	s_sub_i32 s18, s18, s23
	s_mul_i32 s21, s18, s21
	s_sub_i32 s19, s19, s21
	s_add_i32 s20, s20, s19
.LBB0_873:
	s_ashr_i32 s21, s20, 31
	s_lshl_b64 s[22:23], s[20:21], 19
	s_add_u32 s22, s34, s22
	s_addc_u32 s23, s35, s23
	s_and_b64 s[24:25], s[4:5], exec
	s_cselect_b32 s21, s23, s27
	s_cselect_b32 s50, s22, s26
	s_ashr_i32 s19, s18, 31
	s_lshl_b64 s[24:25], s[18:19], 19
	s_add_u32 s24, s36, s24
	s_addc_u32 s25, s37, s25
	s_and_b64 s[30:31], s[4:5], exec
	s_cselect_b32 s19, s25, s29
	s_cselect_b32 s51, s24, s28
	s_add_u32 s26, s26, 0x40080
	s_addc_u32 s27, s27, 0
	s_add_u32 s52, s28, 0x100
	v_mov_b32_e32 v8, 0
	s_addc_u32 s53, s29, 0
	s_mov_b32 s66, -2
	s_waitcnt lgkmcnt(0)
	s_add_u32 s28, s26, 0xfffc0080
	s_addc_u32 s29, s27, -1
	s_cmp_eq_u32 s66, 12
	s_cselect_b32 s31, s21, s29
	s_cselect_b32 s30, s50, s28
	s_cselect_b32 s29, s19, s53
	s_cselect_b32 s28, s51, s52
	v_lshl_add_u64 v[222:223], s[26:27], 0, v[138:139]
	s_add_i32 m0, s9, 0xc000
	s_nop 0
	global_load_lds_dwordx4 v[222:223], off
	v_lshl_add_u64 v[222:223], s[26:27], 0, v[140:141]
	s_add_i32 m0, s9, 0xe000
	s_nop 0
	global_load_lds_dwordx4 v[222:223], off
	s_cmp_eq_u32 s101, 1
	s_cbranch_scc1 .Lpk874_r1
	s_waitcnt vmcnt(8)
	s_branch .Lpk874_j1

;     __host__ __device__ bool next(int i, Unit& u) const {
;         const long L = (long)i * G + c; if (L >= nwg) return false;
;         int wgid = (int)L; { const int q = nwg / NXCD, r = nwg % NXCD, xcd = wgid % NXCD, off = wgid / NXCD; wgid = (xcd < r ? xcd * (q + 1) : r * (q + 1) + (xcd - r) * q) + off; }
;         const int nig = WGM * nN, gid = wgid / nig, fm = gid * WGM, gsz = (nM - fm) < WGM ? (nM - fm) : WGM;
;         u.pm = fm + ((wgid % nig) % gsz); u.pn = (wgid % nig) / gsz; u.idx = i; return true;
; template <class Epi, class Sched, bool ALIGN_EPI>
; __device__ __forceinline__ void gemm_phase(LAS unsigned char* lds, const Gemm g, const Sched& S, const Epi& E) {
;     ...
;         const bool has_next = S.next(ui + 1, nxt);
;         const char* nA = has_next ? (const char*)g.A + (size_t)nxt.pm * tstepA : cA; const char* nB = has_next ? (const char*)g.Bt + (size_t)nxt.pn * tstepB : cB;
.LBB0_1343:
	ds_read_b128 v[136:139], v177
	ds_read_b128 v[140:143], v177 offset:1024
	ds_read_b128 v[144:147], v177 offset:2048
	ds_read_b128 v[148:151], v177 offset:3072
	ds_read_b128 v[180:183], v178
	ds_read_b128 v[184:187], v178 offset:1024
	ds_read_b128 v[188:191], v178 offset:2048
	ds_read_b128 v[192:195], v178 offset:3072
	ds_read_b128 v[196:199], v179
	ds_read_b128 v[200:203], v179 offset:1024
	ds_read_b128 v[204:207], v179 offset:2048
	ds_read_b128 v[208:211], v179 offset:3072
	ds_read_b128 v[212:215], v179 offset:4096
	ds_read_b128 v[216:219], v179 offset:5120
	ds_read_b128 v[220:223], v179 offset:6144
	ds_read_b128 v[224:227], v179 offset:7168
	s_add_i32 s43, s43, 1
	s_mul_i32 s2, s43, s46
	s_mul_hi_u32 s3, s43, s47
	s_add_i32 s3, s3, s2
	s_mul_i32 s2, s43, s47
	s_add_u32 s28, s2, s97
	s_addc_u32 s29, s3, s0
	v_cmp_gt_i64_e32 vcc, s[28:29], v[172:173]
	v_cmp_lt_i64_e64 s[2:3], s[28:29], v[170:171]
	s_cbranch_vccnz .LBB0_1349
	s_ashr_i32 s20, s28, 31
	s_lshr_b32 s20, s20, 29
	s_add_i32 s22, s28, s20
	s_and_b32 s20, s22, -8
	s_sub_i32 s28, s28, s20
	s_cmp_gt_i32 s28, -1
	s_mov_b64 s[20:21], -1
	s_cbranch_scc0 .LBB0_1346
	s_lshl_b32 s29, s28, 6
	s_mov_b64 s[20:21], 0

.LBB0_1349:
	v_mov_b32_e32 v0, 0
	v_lshl_add_u64 v[128:129], s[26:27], 0, v[162:163]
	v_lshl_add_u64 v[130:131], s[26:27], 0, v[164:165]
	v_lshl_add_u64 v[132:133], s[24:25], 0, v[166:167]
	v_lshl_add_u64 v[134:135], s[24:25], 0, v[168:169]
	s_mov_b32 s21, -2
	s_mov_b64 s[28:29], 0
	v_lshl_add_u64 v[230:231], v[130:131], 0, s[28:29]
	s_mov_b32 m0, s50
	v_lshl_add_u64 v[228:229], v[230:231], 0, s[8:9]
	v_lshl_add_u64 v[232:233], v[128:129], 0, s[28:29]
	global_load_lds_dwordx4 v[228:229], off
	v_lshl_add_u64 v[228:229], v[232:233], 0, s[8:9]
	s_mov_b32 m0, s51
	s_nop 0
	global_load_lds_dwordx4 v[228:229], off
	s_waitcnt vmcnt(8)
	s_waitcnt lgkmcnt(0)
	s_barrier
	s_setprio 1
	s_waitcnt lgkmcnt(0)
	v_mfma_f32_16x16x32_bf16 v[124:127], v[136:139], v[196:199], 0
	v_mfma_f32_16x16x32_bf16 v[120:123], v[144:147], v[196:199], 0
	v_mfma_f32_16x16x32_bf16 v[116:119], v[136:139], v[204:207], 0
	v_mfma_f32_16x16x32_bf16 v[112:115], v[144:147], v[204:207], 0
	v_mfma_f32_16x16x32_bf16 v[104:107], v[136:139], v[212:215], 0
	v_mfma_f32_16x16x32_bf16 v[96:99], v[144:147], v[212:215], 0
	v_mfma_f32_16x16x32_bf16 v[84:87], v[136:139], v[220:223], 0
	v_mfma_f32_16x16x32_bf16 v[80:83], v[144:147], v[220:223], 0
	v_mfma_f32_16x16x32_bf16 v[124:127], v[140:143], v[200:203], v[124:127]
	v_mfma_f32_16x16x32_bf16 v[120:123], v[148:151], v[200:203], v[120:123]
	v_mfma_f32_16x16x32_bf16 v[116:119], v[140:143], v[208:211], v[116:119]
	v_mfma_f32_16x16x32_bf16 v[112:115], v[148:151], v[208:211], v[112:115]
	v_mfma_f32_16x16x32_bf16 v[104:107], v[140:143], v[216:219], v[104:107]
	v_mfma_f32_16x16x32_bf16 v[96:99], v[148:151], v[216:219], v[96:99]
	v_mfma_f32_16x16x32_bf16 v[84:87], v[140:143], v[224:227], v[84:87]
	v_mfma_f32_16x16x32_bf16 v[80:83], v[148:151], v[224:227], v[80:83]
	s_setprio 0
	s_setprio 1
	v_mfma_f32_16x16x32_bf16 v[108:111], v[180:183], v[196:199], 0
	v_mfma_f32_16x16x32_bf16 v[100:103], v[188:191], v[196:199], 0
	v_mfma_f32_16x16x32_bf16 v[92:95], v[180:183], v[204:207], 0
	v_mfma_f32_16x16x32_bf16 v[88:91], v[188:191], v[204:207], 0
	v_mfma_f32_16x16x32_bf16 v[76:79], v[180:183], v[212:215], 0
	v_mfma_f32_16x16x32_bf16 v[72:75], v[188:191], v[212:215], 0
	v_mfma_f32_16x16x32_bf16 v[68:71], v[180:183], v[220:223], 0
	v_mfma_f32_16x16x32_bf16 v[64:67], v[188:191], v[220:223], 0
	v_mfma_f32_16x16x32_bf16 v[108:111], v[184:187], v[200:203], v[108:111]
	v_mfma_f32_16x16x32_bf16 v[100:103], v[192:195], v[200:203], v[100:103]
	v_mfma_f32_16x16x32_bf16 v[92:95], v[184:187], v[208:211], v[92:95]
	v_mfma_f32_16x16x32_bf16 v[88:91], v[192:195], v[208:211], v[88:91]
	v_mfma_f32_16x16x32_bf16 v[76:79], v[184:187], v[216:219], v[76:79]
	v_mfma_f32_16x16x32_bf16 v[72:75], v[192:195], v[216:219], v[72:75]
	v_mfma_f32_16x16x32_bf16 v[68:71], v[184:187], v[224:227], v[68:71]
	v_mfma_f32_16x16x32_bf16 v[64:67], v[192:195], v[224:227], v[64:67]
	s_setprio 0
	s_barrier
	v_lshl_add_u64 v[234:235], v[134:135], 0, s[28:29]
	s_add_i32 s53, s48, s38
	v_lshl_add_u64 v[228:229], v[234:235], 0, s[12:13]
	s_mov_b32 m0, s53
	v_lshl_add_u64 v[236:237], v[132:133], 0, s[28:29]
	s_add_i32 s56, s53, 0x2000
	ds_read_b128 v[196:199], v179 offset:16384
	ds_read_b128 v[200:203], v179 offset:17408
	global_load_lds_dwordx4 v[228:229], off
	v_lshl_add_u64 v[228:229], v[236:237], 0, s[12:13]
	s_mov_b32 m0, s56
	s_add_i32 s57, s49, s38
	ds_read_b128 v[204:207], v179 offset:18432
	ds_read_b128 v[208:211], v179 offset:19456
	global_load_lds_dwordx4 v[228:229], off
	v_lshl_add_u64 v[228:229], v[234:235], 0, s[14:15]
	s_mov_b32 m0, s57
	s_add_i32 s58, s57, 0x2000
	ds_read_b128 v[212:215], v179 offset:20480
	global_load_lds_dwordx4 v[228:229], off
	v_lshl_add_u64 v[228:229], v[236:237], 0, s[14:15]
	s_mov_b32 m0, s58
	ds_read_b128 v[216:219], v179 offset:21504
	global_load_lds_dwordx4 v[228:229], off
	v_lshl_add_u64 v[228:229], v[230:231], 0, s[12:13]
	s_mov_b32 m0, s39
	ds_read_b128 v[220:223], v179 offset:22528
	global_load_lds_dwordx4 v[228:229], off
	v_lshl_add_u64 v[228:229], v[232:233], 0, s[12:13]
	s_mov_b32 m0, s40
	ds_read_b128 v[224:227], v179 offset:23552
	global_load_lds_dwordx4 v[228:229], off
	s_waitcnt vmcnt(8)
	s_waitcnt lgkmcnt(0)
	s_barrier
	s_setprio 1
	s_waitcnt lgkmcnt(0)
	v_mfma_f32_16x16x32_bf16 v[60:63], v[136:139], v[196:199], 0
	v_mfma_f32_16x16x32_bf16 v[56:59], v[144:147], v[196:199], 0
	v_mfma_f32_16x16x32_bf16 v[48:51], v[136:139], v[204:207], 0
	v_mfma_f32_16x16x32_bf16 v[40:43], v[144:147], v[204:207], 0
	v_mfma_f32_16x16x32_bf16 v[32:35], v[136:139], v[212:215], 0
	v_mfma_f32_16x16x32_bf16 v[24:27], v[144:147], v[212:215], 0
	v_mfma_f32_16x16x32_bf16 v[16:19], v[136:139], v[220:223], 0
	v_mfma_f32_16x16x32_bf16 v[8:11], v[144:147], v[220:223], 0
	v_mfma_f32_16x16x32_bf16 v[60:63], v[140:143], v[200:203], v[60:63]
	v_mfma_f32_16x16x32_bf16 v[56:59], v[148:151], v[200:203], v[56:59]
	v_mfma_f32_16x16x32_bf16 v[48:51], v[140:143], v[208:211], v[48:51]
	v_mfma_f32_16x16x32_bf16 v[40:43], v[148:151], v[208:211], v[40:43]
	v_mfma_f32_16x16x32_bf16 v[32:35], v[140:143], v[216:219], v[32:35]
	v_mfma_f32_16x16x32_bf16 v[24:27], v[148:151], v[216:219], v[24:27]
	v_mfma_f32_16x16x32_bf16 v[16:19], v[140:143], v[224:227], v[16:19]
	v_mfma_f32_16x16x32_bf16 v[8:11], v[148:151], v[224:227], v[8:11]
	s_setprio 0
	s_setprio 1
	v_mfma_f32_16x16x32_bf16 v[52:55], v[180:183], v[196:199], 0
	v_mfma_f32_16x16x32_bf16 v[44:47], v[188:191], v[196:199], 0
	v_mfma_f32_16x16x32_bf16 v[36:39], v[180:183], v[204:207], 0
	v_mfma_f32_16x16x32_bf16 v[28:31], v[188:191], v[204:207], 0
	v_mfma_f32_16x16x32_bf16 v[20:23], v[180:183], v[212:215], 0
	v_mfma_f32_16x16x32_bf16 v[12:15], v[188:191], v[212:215], 0
	v_mfma_f32_16x16x32_bf16 v[4:7], v[180:183], v[220:223], 0
	v_mfma_f32_16x16x32_bf16 v[0:3], v[188:191], v[220:223], 0
	v_mfma_f32_16x16x32_bf16 v[52:55], v[184:187], v[200:203], v[52:55]
	v_mfma_f32_16x16x32_bf16 v[44:47], v[192:195], v[200:203], v[44:47]
	v_mfma_f32_16x16x32_bf16 v[36:39], v[184:187], v[208:211], v[36:39]
	v_mfma_f32_16x16x32_bf16 v[28:31], v[192:195], v[208:211], v[28:31]
	v_mfma_f32_16x16x32_bf16 v[20:23], v[184:187], v[216:219], v[20:23]
	v_mfma_f32_16x16x32_bf16 v[12:15], v[192:195], v[216:219], v[12:15]
	v_mfma_f32_16x16x32_bf16 v[4:7], v[184:187], v[224:227], v[4:7]
	v_mfma_f32_16x16x32_bf16 v[0:3], v[192:195], v[224:227], v[0:3]
	s_setprio 0
	s_barrier
	s_branch .Lpk1350_seg3

;     __host__ __device__ bool next(int i, Unit& u) const {
;         const long L = (long)i * G + c; if (L >= nwg) return false;
;         int wgid = (int)L; { const int q = nwg / NXCD, r = nwg % NXCD, xcd = wgid % NXCD, off = wgid / NXCD; wgid = (xcd < r ? xcd * (q + 1) : r * (q + 1) + (xcd - r) * q) + off; }
;         const int nig = WGM * nN, gid = wgid / nig, fm = gid * WGM, gsz = (nM - fm) < WGM ? (nM - fm) : WGM;
;         u.pm = fm + ((wgid % nig) % gsz); u.pn = (wgid % nig) / gsz; u.idx = i; return true;
; template <class Epi, class Sched, bool ALIGN_EPI>
; __device__ __forceinline__ void gemm_phase(LAS unsigned char* lds, const Gemm g, const Sched& S, const Epi& E) {
;     ...
;         const bool has_next = S.next(ui + 1, nxt);
;         const char* nA = has_next ? (const char*)g.A + (size_t)nxt.pm * tstepA : cA; const char* nB = has_next ? (const char*)g.Bt + (size_t)nxt.pn * tstepB : cB;
.LBB0_1450:
	ds_read_b128 v[128:131], v191
	ds_read_b128 v[132:135], v191 offset:1024
	ds_read_b128 v[136:139], v191 offset:2048
	ds_read_b128 v[140:143], v191 offset:3072
	ds_read_b128 v[144:147], v192
	ds_read_b128 v[148:151], v192 offset:1024
	ds_read_b128 v[170:173], v192 offset:2048
	ds_read_b128 v[174:177], v192 offset:3072
	ds_read_b128 v[178:181], v193
	ds_read_b128 v[182:185], v193 offset:1024
	ds_read_b128 v[196:199], v193 offset:2048
	ds_read_b128 v[200:203], v193 offset:3072
	ds_read_b128 v[204:207], v193 offset:4096
	ds_read_b128 v[208:211], v193 offset:5120
	ds_read_b128 v[212:215], v193 offset:6144
	ds_read_b128 v[216:219], v193 offset:7168
	s_add_i32 s41, s41, 1
	s_mul_i32 s4, s41, s44
	s_mul_hi_u32 s5, s41, s45
	s_add_i32 s5, s5, s4
	s_mul_i32 s4, s41, s45
	s_add_u32 s22, s4, s97
	s_addc_u32 s23, s5, s46
	v_cmp_gt_i64_e32 vcc, s[22:23], v[168:169]
	v_cmp_lt_i64_e64 s[4:5], s[22:23], v[166:167]
	s_cbranch_vccnz .LBB0_1456
	s_ashr_i32 s18, s22, 31
	s_lshr_b32 s18, s18, 29
	s_add_i32 s20, s22, s18
	s_and_b32 s18, s20, -8
	s_sub_i32 s21, s22, s18
	s_cmp_gt_i32 s21, -1
	s_mov_b64 s[18:19], -1
	s_cbranch_scc0 .LBB0_1453
	s_lshl_b32 s22, s21, 6
	s_mov_b64 s[18:19], 0

.LBB0_1456:
	s_ashr_i32 s21, s20, 31
	s_lshl_b64 s[22:23], s[20:21], 20
	s_add_u32 s22, s72, s22
	s_addc_u32 s23, s73, s23
	s_and_b64 s[24:25], s[4:5], exec
	s_cselect_b32 s21, s23, s31
	s_cselect_b32 s27, s22, s30
	s_ashr_i32 s19, s18, 31
	s_lshl_b64 s[24:25], s[18:19], 19
	s_add_u32 s24, s0, s24
	s_addc_u32 s25, s1, s25
	s_and_b64 s[36:37], s[4:5], exec
	s_cselect_b32 s19, s25, s35
	s_cselect_b32 s49, s24, s34
	s_add_u32 s30, s30, 0x80080
	s_addc_u32 s31, s31, 0
	s_add_u32 s50, s34, 0x100
	v_mov_b32_e32 v0, 0
	s_addc_u32 s51, s35, 0
	s_mov_b32 s52, -2
	s_waitcnt lgkmcnt(0)
	s_add_u32 s34, s30, 0xfff80080
	s_addc_u32 s35, s31, -1
	s_cmp_eq_u32 s52, 12
	s_cselect_b32 s37, s21, s35
	s_cselect_b32 s36, s27, s34
	s_cselect_b32 s35, s19, s51
	s_cselect_b32 s34, s49, s50
	v_lshl_add_u64 v[186:187], s[30:31], 0, v[162:163]
	s_add_i32 m0, s29, 0xc000
	s_nop 0
	global_load_lds_dwordx4 v[186:187], off
	v_lshl_add_u64 v[186:187], s[30:31], 0, v[164:165]
	s_add_i32 m0, s29, 0xe000
	s_nop 0
	global_load_lds_dwordx4 v[186:187], off
	s_cmp_eq_u32 s101, 1
	s_cbranch_scc1 .Lpk1457_r1
	s_waitcnt vmcnt(8)
	s_branch .Lpk1457_j1

; template <class Epi, class Sched, bool ALIGN_EPI>
; __device__ __forceinline__ void gemm_phase(LAS unsigned char* lds, const Gemm g, const Sched& S, const Epi& E) {
;     ...
;         const bool has_next = S.next(ui + 1, nxt);
;         const char* nA = has_next ? (const char*)g.A + (size_t)nxt.pm * tstepA : cA; const char* nB = has_next ? (const char*)g.Bt + (size_t)nxt.pn * tstepB : cB;
.LBB0_1610:
	ds_read_b128 v[154:157], v148
	ds_read_b128 v[158:161], v148 offset:1024
	ds_read_b128 v[162:165], v148 offset:2048
	ds_read_b128 v[166:169], v148 offset:3072
	ds_read_b128 v[170:173], v149
	ds_read_b128 v[174:177], v149 offset:1024
	ds_read_b128 v[178:181], v149 offset:2048
	ds_read_b128 v[182:185], v149 offset:3072
	ds_read_b128 v[186:189], v150
	ds_read_b128 v[190:193], v150 offset:1024
	ds_read_b128 v[194:197], v150 offset:2048
	ds_read_b128 v[198:201], v150 offset:3072
	ds_read_b128 v[202:205], v150 offset:4096
	ds_read_b128 v[206:209], v150 offset:5120
	ds_read_b128 v[210:213], v150 offset:6144
	ds_read_b128 v[214:217], v150 offset:7168
	s_add_i32 s41, s41, 1
	s_mul_i32 s2, s41, s0
	s_mul_hi_u32 s3, s41, s76
	s_add_i32 s3, s3, s2
	s_mul_i32 s2, s41, s76
	s_add_u32 s14, s2, s97
	s_addc_u32 s15, s3, s1
	v_cmp_gt_i64_e32 vcc, s[14:15], v[142:143]
	v_cmp_lt_i64_e64 s[2:3], s[14:15], v[140:141]
	s_cbranch_vccnz .LBB0_1612
	s_ashr_i32 s10, s14, 31
	s_lshr_b32 s10, s10, 29
	s_add_i32 s10, s14, s10
	s_ashr_i32 s11, s10, 3
	s_and_b32 s10, s10, -8
	s_sub_i32 s10, s14, s10
	s_cmp_lt_i32 s10, 0
	s_cselect_b32 s12, s31, 0x160
	s_mul_i32 s10, s10, s12
	s_add_i32 s10, s10, s11
	s_mul_hi_i32 s11, s10, 0x2e8ba2e9
	s_lshr_b32 s12, s11, 31
	s_ashr_i32 s11, s11, 4
	s_add_i32 s11, s11, s12
	s_lshl_b32 s12, s11, 2
	s_sub_i32 s13, 0x80, s12
	s_min_i32 s13, s13, 4
	s_abs_i32 s14, s13
	v_cvt_f32_u32_e32 v0, s14
	s_sub_i32 s16, 0, s14
	s_mulk_i32 s11, 0x58
	s_sub_i32 s11, s10, s11
	v_rcp_iflag_f32_e32 v0, v0
	s_abs_i32 s10, s11
	s_xor_b32 s15, s11, s13
	s_ashr_i32 s15, s15, 31
	v_mul_f32_e32 v0, 0x4f7ffffe, v0
	v_cvt_u32_f32_e32 v0, v0
	s_mov_b32 s42, s41
	v_readfirstlane_b32 s17, v0
	s_mul_i32 s16, s16, s17
	s_mul_hi_u32 s16, s17, s16
	s_add_i32 s17, s17, s16
	s_mul_hi_u32 s16, s10, s17
	s_mul_i32 s17, s16, s14
	s_sub_i32 s10, s10, s17
	s_add_i32 s24, s16, 1
	s_sub_i32 s17, s10, s14
	s_cmp_ge_u32 s10, s14
	s_cselect_b32 s16, s24, s16
	s_cselect_b32 s10, s17, s10
	s_add_i32 s17, s16, 1
	s_cmp_ge_u32 s10, s14
	s_cselect_b32 s10, s17, s16
	s_xor_b32 s10, s10, s15
	s_sub_i32 s10, s10, s15
	s_mul_i32 s13, s10, s13
	s_sub_i32 s11, s11, s13
	s_add_i32 s12, s12, s11
.LBB0_1612:
	s_ashr_i32 s13, s12, 31
	s_lshl_b64 s[14:15], s[12:13], 19
	s_add_u32 s14, s27, s14
	s_addc_u32 s15, s28, s15
	s_and_b64 s[16:17], s[2:3], exec
	s_cselect_b32 s13, s15, s21
	s_cselect_b32 s45, s14, s20
	s_ashr_i32 s11, s10, 31
	s_lshl_b64 s[16:17], s[10:11], 19
	s_add_u32 s16, s29, s16
	s_addc_u32 s17, s30, s17
	s_and_b64 s[24:25], s[2:3], exec
	s_cselect_b32 s11, s17, s23
	s_cselect_b32 s46, s16, s22
	s_add_u32 s20, s20, 0x40080
	s_addc_u32 s21, s21, 0
	s_add_u32 s47, s22, 0x100
	v_mov_b32_e32 v0, 0
	s_addc_u32 s48, s23, 0
	s_mov_b32 s49, -2
	s_add_u32 s22, s20, 0xfffc0080
	s_addc_u32 s23, s21, -1
	s_cmp_eq_u32 s49, 12
	s_cselect_b32 s25, s13, s23
	s_cselect_b32 s24, s45, s22
	s_cselect_b32 s23, s11, s48
	s_cselect_b32 s22, s46, s47
	v_lshl_add_u64 v[218:219], s[20:21], 0, v[136:137]
	s_add_i32 m0, s19, 0xc000
	s_nop 0
	global_load_lds_dwordx4 v[218:219], off
	v_lshl_add_u64 v[218:219], s[20:21], 0, v[138:139]
	s_add_i32 m0, s19, 0xe000
	s_nop 0
	global_load_lds_dwordx4 v[218:219], off
	s_cmp_eq_u32 s101, 1
	s_cbranch_scc1 .Lpk1613_r1
	s_waitcnt vmcnt(8)
	s_branch .Lpk1613_j1

;     __host__ __device__ bool next(int i, Unit& u) const {
;         const long L = (long)i * G + c; if (L >= nwg) return false;
;         int wgid = (int)L; { const int q = nwg / NXCD, r = nwg % NXCD, xcd = wgid % NXCD, off = wgid / NXCD; wgid = (xcd < r ? xcd * (q + 1) : r * (q + 1) + (xcd - r) * q) + off; }
;         const int nig = WGM * nN, gid = wgid / nig, fm = gid * WGM, gsz = (nM - fm) < WGM ? (nM - fm) : WGM;
;         u.pm = fm + ((wgid % nig) % gsz); u.pn = (wgid % nig) / gsz; u.idx = i; return true;
; template <class Epi, class Sched, bool ALIGN_EPI>
; __device__ __forceinline__ void gemm_phase(LAS unsigned char* lds, const Gemm g, const Sched& S, const Epi& E) {
;     ...
;         const bool has_next = S.next(ui + 1, nxt);
;         const char* nA = has_next ? (const char*)g.A + (size_t)nxt.pm * tstepA : cA; const char* nB = has_next ? (const char*)g.Bt + (size_t)nxt.pn * tstepB : cB;
.LBB0_1711:
	ds_read_b128 v[128:131], v199
	ds_read_b128 v[132:135], v199 offset:1024
	ds_read_b128 v[136:139], v199 offset:2048
	ds_read_b128 v[140:143], v199 offset:3072
	ds_read_b128 v[144:147], v200
	ds_read_b128 v[148:151], v200 offset:1024
	ds_read_b128 v[168:171], v200 offset:2048
	ds_read_b128 v[172:175], v200 offset:3072
	ds_read_b128 v[176:179], v201
	ds_read_b128 v[180:183], v201 offset:1024
	ds_read_b128 v[184:187], v201 offset:2048
	ds_read_b128 v[188:191], v201 offset:3072
	ds_read_b128 v[192:195], v201 offset:4096
	ds_read_b128 v[204:207], v201 offset:5120
	ds_read_b128 v[208:211], v201 offset:6144
	ds_read_b128 v[212:215], v201 offset:7168
	s_add_i32 s34, s34, 1
	s_mul_i32 s4, s34, s39
	s_mul_hi_u32 s5, s34, s76
	s_add_i32 s5, s5, s4
	s_mul_i32 s4, s34, s76
	s_add_u32 s4, s4, s97
	s_addc_u32 s5, s5, s40
	v_cmp_gt_i64_e32 vcc, s[4:5], v[166:167]
	v_cmp_lt_i64_e64 s[6:7], s[4:5], v[164:165]
	s_cbranch_vccnz .LBB0_1717
	s_ashr_i32 s5, s4, 31
	s_lshr_b32 s5, s5, 29
	s_add_i32 s18, s4, s5
	s_and_b32 s5, s18, -8
	s_sub_i32 s19, s4, s5
	s_cmp_gt_i32 s19, -1
	s_mov_b64 s[4:5], -1
	s_cbranch_scc0 .LBB0_1714
	s_lshl_b32 s20, s19, 6
	s_mov_b64 s[4:5], 0

.LBB0_1721:
	s_add_u32 s6, s24, 0xb0080
	s_addc_u32 s7, s25, 0
	s_add_u32 s48, s22, 0x100
	v_mov_b32_e32 v0, 0
	s_addc_u32 s49, s23, 0
	s_mov_b32 s50, -2
	s_add_u32 s22, s6, 0xfff50080
	s_addc_u32 s23, s7, -1
	s_cmp_eq_u32 s50, 40
	s_cselect_b32 s25, s19, s23
	s_cselect_b32 s24, s18, s22
	s_cselect_b32 s23, s21, s49
	s_cselect_b32 s22, s20, s48
	v_lshl_add_u64 v[216:217], s[6:7], 0, v[152:153]
	s_add_i32 m0, s29, 0xc000
	s_nop 0
	global_load_lds_dwordx4 v[216:217], off
	v_lshl_add_u64 v[216:217], s[6:7], 0, v[162:163]
	s_add_i32 m0, s29, 0xe000
	s_nop 0
	global_load_lds_dwordx4 v[216:217], off
	s_waitcnt vmcnt(8)
	s_waitcnt lgkmcnt(0)
	s_barrier
	s_setprio 1
	s_waitcnt lgkmcnt(0)
	v_mfma_f32_16x16x32_bf16 v[124:127], v[128:131], v[176:179], 0
	v_mfma_f32_16x16x32_bf16 v[120:123], v[136:139], v[176:179], 0
	v_mfma_f32_16x16x32_bf16 v[108:111], v[128:131], v[184:187], 0
	v_mfma_f32_16x16x32_bf16 v[104:107], v[136:139], v[184:187], 0
	v_mfma_f32_16x16x32_bf16 v[92:95], v[128:131], v[192:195], 0
	v_mfma_f32_16x16x32_bf16 v[88:91], v[136:139], v[192:195], 0
	v_mfma_f32_16x16x32_bf16 v[76:79], v[128:131], v[208:211], 0
	v_mfma_f32_16x16x32_bf16 v[72:75], v[136:139], v[208:211], 0
	v_mfma_f32_16x16x32_bf16 v[124:127], v[132:135], v[180:183], v[124:127]
	v_mfma_f32_16x16x32_bf16 v[120:123], v[140:143], v[180:183], v[120:123]
	v_mfma_f32_16x16x32_bf16 v[108:111], v[132:135], v[188:191], v[108:111]
	v_mfma_f32_16x16x32_bf16 v[104:107], v[140:143], v[188:191], v[104:107]
	v_mfma_f32_16x16x32_bf16 v[92:95], v[132:135], v[204:207], v[92:95]
	v_mfma_f32_16x16x32_bf16 v[88:91], v[140:143], v[204:207], v[88:91]
	v_mfma_f32_16x16x32_bf16 v[76:79], v[132:135], v[212:215], v[76:79]
	v_mfma_f32_16x16x32_bf16 v[72:75], v[140:143], v[212:215], v[72:75]
	s_setprio 0
	s_setprio 1
	v_mfma_f32_16x16x32_bf16 v[116:119], v[144:147], v[176:179], 0
	v_mfma_f32_16x16x32_bf16 v[112:115], v[168:171], v[176:179], 0
	v_mfma_f32_16x16x32_bf16 v[100:103], v[144:147], v[184:187], 0
	v_mfma_f32_16x16x32_bf16 v[96:99], v[168:171], v[184:187], 0
	v_mfma_f32_16x16x32_bf16 v[84:87], v[144:147], v[192:195], 0
	v_mfma_f32_16x16x32_bf16 v[80:83], v[168:171], v[192:195], 0
	v_mfma_f32_16x16x32_bf16 v[68:71], v[144:147], v[208:211], 0
	v_mfma_f32_16x16x32_bf16 v[64:67], v[168:171], v[208:211], 0
	v_mfma_f32_16x16x32_bf16 v[116:119], v[148:151], v[180:183], v[116:119]
	v_mfma_f32_16x16x32_bf16 v[112:115], v[172:175], v[180:183], v[112:115]
	v_mfma_f32_16x16x32_bf16 v[100:103], v[148:151], v[188:191], v[100:103]
	v_mfma_f32_16x16x32_bf16 v[96:99], v[172:175], v[188:191], v[96:99]
	v_mfma_f32_16x16x32_bf16 v[84:87], v[148:151], v[204:207], v[84:87]
	v_mfma_f32_16x16x32_bf16 v[80:83], v[172:175], v[204:207], v[80:83]
	v_mfma_f32_16x16x32_bf16 v[68:71], v[148:151], v[212:215], v[68:71]
	v_mfma_f32_16x16x32_bf16 v[64:67], v[172:175], v[212:215], v[64:67]
	s_setprio 0
	s_barrier
	s_add_i32 s51, s41, s28
	v_lshl_add_u64 v[216:217], s[22:23], 0, v[156:157]
	s_mov_b32 m0, s51
	ds_read_b128 v[176:179], v201 offset:16384
	ds_read_b128 v[180:183], v201 offset:17408
	global_load_lds_dwordx4 v[216:217], off
	s_add_i32 m0, s51, 0x2000
	s_add_u32 s52, s22, 0xb0000
	v_lshl_add_u64 v[218:219], s[22:23], 0, v[160:161]
	s_addc_u32 s53, s23, 0
	s_add_i32 s51, s42, s28
	ds_read_b128 v[184:187], v201 offset:18432
	ds_read_b128 v[188:191], v201 offset:19456
	global_load_lds_dwordx4 v[218:219], off
	v_lshl_add_u64 v[220:221], s[52:53], 0, v[156:157]
	s_mov_b32 m0, s51
	v_lshl_add_u64 v[222:223], s[24:25], 0, v[158:159]
	ds_read_b128 v[192:195], v201 offset:20480
	global_load_lds_dwordx4 v[220:221], off
	v_lshl_add_u64 v[220:221], s[52:53], 0, v[160:161]
	s_add_i32 m0, s51, 0x2000
	ds_read_b128 v[204:207], v201 offset:21504
	global_load_lds_dwordx4 v[220:221], off
	v_lshl_add_u64 v[220:221], s[24:25], 0, v[154:155]
	s_mov_b32 m0, s29
	ds_read_b128 v[208:211], v201 offset:22528
	global_load_lds_dwordx4 v[220:221], off
	s_mov_b32 m0, s30
	ds_read_b128 v[212:215], v201 offset:23552
	global_load_lds_dwordx4 v[222:223], off
	s_waitcnt vmcnt(8)
	s_waitcnt lgkmcnt(0)
	s_barrier
	s_setprio 1
	s_waitcnt lgkmcnt(0)
	v_mfma_f32_16x16x32_bf16 v[60:63], v[128:131], v[176:179], 0
	v_mfma_f32_16x16x32_bf16 v[56:59], v[136:139], v[176:179], 0
	v_mfma_f32_16x16x32_bf16 v[44:47], v[128:131], v[184:187], 0
	v_mfma_f32_16x16x32_bf16 v[40:43], v[136:139], v[184:187], 0
	v_mfma_f32_16x16x32_bf16 v[28:31], v[128:131], v[192:195], 0
	v_mfma_f32_16x16x32_bf16 v[24:27], v[136:139], v[192:195], 0
	v_mfma_f32_16x16x32_bf16 v[12:15], v[128:131], v[208:211], 0
	v_mfma_f32_16x16x32_bf16 v[8:11], v[136:139], v[208:211], 0
	v_mfma_f32_16x16x32_bf16 v[60:63], v[132:135], v[180:183], v[60:63]
	v_mfma_f32_16x16x32_bf16 v[56:59], v[140:143], v[180:183], v[56:59]
	v_mfma_f32_16x16x32_bf16 v[44:47], v[132:135], v[188:191], v[44:47]
	v_mfma_f32_16x16x32_bf16 v[40:43], v[140:143], v[188:191], v[40:43]
	v_mfma_f32_16x16x32_bf16 v[28:31], v[132:135], v[204:207], v[28:31]
	v_mfma_f32_16x16x32_bf16 v[24:27], v[140:143], v[204:207], v[24:27]
	v_mfma_f32_16x16x32_bf16 v[12:15], v[132:135], v[212:215], v[12:15]
	v_mfma_f32_16x16x32_bf16 v[8:11], v[140:143], v[212:215], v[8:11]
	s_setprio 0
	s_setprio 1
	v_mfma_f32_16x16x32_bf16 v[52:55], v[144:147], v[176:179], 0
	v_mfma_f32_16x16x32_bf16 v[48:51], v[168:171], v[176:179], 0
	v_mfma_f32_16x16x32_bf16 v[36:39], v[144:147], v[184:187], 0
	v_mfma_f32_16x16x32_bf16 v[32:35], v[168:171], v[184:187], 0
	v_mfma_f32_16x16x32_bf16 v[20:23], v[144:147], v[192:195], 0
	v_mfma_f32_16x16x32_bf16 v[16:19], v[168:171], v[192:195], 0
	v_mfma_f32_16x16x32_bf16 v[4:7], v[144:147], v[208:211], 0
	v_mfma_f32_16x16x32_bf16 v[0:3], v[168:171], v[208:211], 0
	v_mfma_f32_16x16x32_bf16 v[52:55], v[148:151], v[180:183], v[52:55]
	v_mfma_f32_16x16x32_bf16 v[48:51], v[172:175], v[180:183], v[48:51]
	v_mfma_f32_16x16x32_bf16 v[36:39], v[148:151], v[188:191], v[36:39]
	v_mfma_f32_16x16x32_bf16 v[32:35], v[172:175], v[188:191], v[32:35]
	v_mfma_f32_16x16x32_bf16 v[20:23], v[148:151], v[204:207], v[20:23]
	v_mfma_f32_16x16x32_bf16 v[16:19], v[172:175], v[204:207], v[16:19]
	v_mfma_f32_16x16x32_bf16 v[4:7], v[148:151], v[212:215], v[4:7]
	v_mfma_f32_16x16x32_bf16 v[0:3], v[172:175], v[212:215], v[0:3]
	s_setprio 0
	s_barrier
	s_branch .Lpk1722_seg3
